# v32 with the GEMM job prologue issuing both k-tiles' 14 DMA loads before the first wait and barrier
# baseline (speedup 1.0000x reference)
.LBB0_261:
	s_add_i32 s88, s70, 0x18000
	s_or_b32 s18, s44, 0x80
	s_mov_b32 s48, s94
	s_mov_b32 s50, s78
	s_mov_b32 s51, s79
	s_mov_b32 m0, s88
	s_add_i32 s82, s70, 0x1a000
	buffer_load_dwordx4 v218, s[48:51], s18 offen lds
	s_mov_b32 m0, s82
	s_add_i32 s83, s70, 0x8000
	buffer_load_dwordx4 v220, s[48:51], s18 offen lds
	s_or_b32 s18, s45, 0x80
	s_mov_b32 s76, s46
	s_mov_b32 m0, s83
	s_add_i32 s89, s70, 0xa000
	buffer_load_dwordx4 v217, s[76:79], s18 offen lds
	s_mov_b32 m0, s89
	s_add_i32 s58, s70, 0x1c000
	buffer_load_dwordx4 v219, s[76:79], s18 offen lds
	s_bitset1_b32 s3, 7
	s_mov_b32 m0, s58
	s_add_i32 s59, s70, 0x1e000
	buffer_load_dwordx4 v218, s[48:51], s3 offen lds
	s_mov_b32 m0, s59
	v_or_b32_e32 v221, s42, v162
	buffer_load_dwordx4 v220, s[48:51], s3 offen lds
	s_waitcnt vmcnt(8)
	s_barrier
	s_ashr_i32 s3, s54, 31
	s_lshr_b32 s3, s3, 26
	s_add_i32 s3, s54, s3
	v_writelane_b32 v255, s54, 40
	s_ashr_i32 s54, s3, 6
	v_lshlrev_b32_e32 v0, 6, v221
	s_movk_i32 s3, 0x3c0
	v_lshlrev_b32_e32 v1, 2, v221
	v_and_or_b32 v0, v0, s3, v213
	s_lshl_b32 s1, s1, 13
	v_and_b32_e32 v1, 32, v1
	v_bitop3_b32 v0, v0, s1, v1 bitop3:0xde
	s_lshl_b32 s1, s2, 5
	s_and_b32 s2, s1, 0x60
	s_add_i32 s55, s54, -2
	s_add_i32 s96, s70, 0xc000
	s_cmpk_lt_u32 s0, 0x100
	s_cselect_b64 s[20:21], -1, 0
	s_ashr_i32 s43, s42, 31
	s_add_i32 s97, s70, 0xe000
	s_ashr_i32 s35, s34, 31
	s_lshl_b64 s[0:1], s[42:43], 3
	s_add_u32 s0, s40, s0
	s_addc_u32 s1, s41, s1
	s_lshl_b32 s18, s24, 2
	s_abs_i32 s19, s18
	v_cvt_f32_u32_e32 v1, s19
	v_lshl_or_b32 v2, s2, 7, v214
	v_lshl_add_u64 v[164:165], s[0:1], 0, v[156:157]
	v_or_b32_e32 v222, s2, v212
	v_rcp_iflag_f32_e32 v1, v1
	s_sub_i32 s1, 0, s19
	s_waitcnt vmcnt(6)
	s_lshl_b32 s60, s24, 3
	v_mul_f32_e32 v1, 0x4f7ffffe, v1
	v_cvt_u32_f32_e32 v1, v1
	s_bfe_i32 s61, s24, 0x1001d
	s_mov_b32 s0, 0
	v_add_u32_e32 v223, 0, v2
	v_readfirstlane_b32 s2, v1
	s_mul_i32 s1, s1, s2
	s_mul_hi_u32 s1, s2, s1
	s_add_i32 s1, s2, s1
	v_add_u32_e32 v224, 0, v0
	s_barrier
	s_branch .LBB0_265
